# merge GEMM epilogues: the 64 flat_load/flat_store_dwordx4 on the per-workgroup scratch slab become global_load/global_store (no LDS-aperture path, no lgkmcnt coupling); on top of v57
# baseline (speedup 1.0000x reference)
; #define PG8_LDA(dst, b, h) do { _Pragma("unroll") for (int m = 0; m < 4; ++m) _Pragma("unroll") for (int k = 0; k < 2; ++k) dst[m][k] = *(const LAS bf16x8*)(lds + PG8_SA(b, h) + aoff + m * 2048 + k * 1024); } while (0)
; #define PG8_LDB(dst, b, h) do { _Pragma("unroll") for (int n = 0; n < 2; ++n) _Pragma("unroll") for (int k = 0; k < 2; ++k) dst[n][k] = *(const LAS bf16x8*)(lds + PG8_SB(b, h) + boff + n * 2048 + k * 1024); } while (0)
; #define PG8_MMA(ai, bj, At, Bt_) do { __builtin_amdgcn_s_setprio(1); _Pragma("unroll") for (int m = 0; m < 4; ++m) _Pragma("unroll") for (int n = 0; n < 2; ++n) _Pragma("unroll") for (int k = 0; k < 2; ++k) \
;     acc[ai][bj][m][n] = __builtin_amdgcn_mfma_f32_16x16x32_bf16(Bt_[n][k], At[m][k], acc[ai][bj][m][n], 0, 0, 0); __builtin_amdgcn_s_setprio(0); } while (0)
; #define PG8_WAIT_L(n) asm volatile("s_waitcnt lgkmcnt(" #n ")" ::: "memory")
; #define PG8_BAR __builtin_amdgcn_s_barrier()
; #define PG8_SCHED __builtin_amdgcn_sched_barrier(0)
; #define PG8_STA(bufoff, gbase, ld2) PG8_STAGE3(bufoff, gbase, ld2, R0, R1)
; #define PG8_STB(bufoff, gbase, ld2) PG8_STAGE3(bufoff, gbase, ld2, Rb0, Rb1)
; #define PG8_LDA(dst, b, h) do { _Pragma("unroll") for (int m = 0; m < 4; ++m) _Pragma("unroll") for (int k = 0; k < 2; ++k) dst[m][k] = *(const LAS bf16x8*)(lds + PG8_SA(b, h) + aoff + m * 2048 + k * 1024); } while (0)
; template <class Sched, class Epi>
; DI void gemm_stream(char* smem, const Sched& S_, const Epi& E) {
;     ...
;       const bool last = (t == nt - 2);
;       const char* a1 = cA + (size_t)(t + 1) * kstep;
;       const char* a2 = last ? nA : cA + (size_t)(t + 2) * kstep; const char* b2 = last ? nB : cB + (size_t)(t + 2) * kstep;
;       const char* a3 = a2 + kstep; const char* b3 = b2 + kstep;
;       const int xa2 = (last ? nxt.lda : cur.lda) * 2, xb2 = (last ? nxt.ldb : cur.ldb) * 2;
;       const size_t xhA = (size_t)HALF * xa2, xhB = (size_t)HALF * xb2;
;       PG8_LDB(B0, 0, 0); PG8_SCHED; PG8_LDA(At, 0, 0); PG8_STA(PG8_SA(1, 1), a1 + hA, la2);
;       PG8_WAIT_L(8); PG8_BAR; PG8_WAIT_L(0); PG8_MMA(0, 0, At, B0); PG8_BAR; PG8_SCHED;
;       PG8_LDB(B1, 0, 1); PG8_STB(PG8_SB(0, 0), b2, xb2);
;       PG8_BAR; PG8_WAIT_L(0); PG8_MMA(0, 1, At, B1); PG8_BAR;
;       PG8_LDA(At, 0, 1); PG8_STA(PG8_SA(0, 0), a2, xa2);
;       PG8_BAR; PG8_WAIT_L(0); PG8_MMA(1, 0, At, B0); PG8_BAR; PG8_SCHED;
.LBB0_1166:
	s_add_i32 s53, s46, 2
	s_add_u32 s50, s44, 0x80
	s_addc_u32 s47, s45, 0
	s_cmp_eq_u32 s62, s46
	s_cselect_b32 s47, s41, s47
	s_cselect_b32 s46, s40, s50
	s_cselect_b32 s50, s13, s20
	s_cselect_b32 s51, s3, s16
	s_cselect_b32 s89, s1, s52
	s_cselect_b32 s88, s0, s63
	s_add_i32 s64, 0, 0x10000
	v_add_u32_e32 v144, s64, v239
	ds_read_b128 v[132:135], v144
	ds_read_b128 v[136:139], v144 offset:1024
	ds_read_b128 v[140:143], v144 offset:2048
	ds_read_b128 v[144:147], v144 offset:3072
	s_lshl_b32 vcc_lo, s50, 1
	s_lshl_b32 s90, s51, 1
	s_ashr_i32 vcc_hi, vcc_lo, 31
	s_ashr_i32 s91, s90, 31
	s_lshl_b64 s[50:51], vcc, 7
	v_lshl_add_u64 v[180:181], s[44:45], 0, v[128:129]
	s_add_i32 m0, s39, 0xc000
	ds_read_b128 v[148:151], v241
	ds_read_b128 v[152:155], v241 offset:1024
	ds_read_b128 v[156:159], v241 offset:2048
	ds_read_b128 v[160:163], v241 offset:3072
	ds_read_b128 v[164:167], v241 offset:4096
	ds_read_b128 v[168:171], v241 offset:5120
	ds_read_b128 v[172:175], v241 offset:6144
	ds_read_b128 v[176:179], v241 offset:7168
	global_load_lds_dwordx4 v[180:181], off
	v_lshl_add_u64 v[180:181], s[44:45], 0, v[130:131]
	s_add_i32 m0, s39, 0xe000
	s_nop 0
	global_load_lds_dwordx4 v[180:181], off
	s_waitcnt lgkmcnt(8)
	s_barrier
	s_waitcnt lgkmcnt(0)
	s_setprio 1
	s_waitcnt lgkmcnt(0)
	v_mfma_f32_16x16x32_bf16 v[124:127], v[132:135], v[148:151], v[124:127]
	v_mfma_f32_16x16x32_bf16 v[120:123], v[140:143], v[148:151], v[120:123]
	v_mfma_f32_16x16x32_bf16 v[116:119], v[132:135], v[156:159], v[116:119]
	v_mfma_f32_16x16x32_bf16 v[112:115], v[140:143], v[156:159], v[112:115]
	v_mfma_f32_16x16x32_bf16 v[100:103], v[132:135], v[164:167], v[100:103]
	v_mfma_f32_16x16x32_bf16 v[96:99], v[140:143], v[164:167], v[96:99]
	v_mfma_f32_16x16x32_bf16 v[84:87], v[132:135], v[172:175], v[84:87]
	v_mfma_f32_16x16x32_bf16 v[80:83], v[140:143], v[172:175], v[80:83]
	v_mfma_f32_16x16x32_bf16 v[124:127], v[136:139], v[152:155], v[124:127]
	v_mfma_f32_16x16x32_bf16 v[120:123], v[144:147], v[152:155], v[120:123]
	v_mfma_f32_16x16x32_bf16 v[116:119], v[136:139], v[160:163], v[116:119]
	v_mfma_f32_16x16x32_bf16 v[112:115], v[144:147], v[160:163], v[112:115]
	v_mfma_f32_16x16x32_bf16 v[100:103], v[136:139], v[168:171], v[100:103]
	v_mfma_f32_16x16x32_bf16 v[96:99], v[144:147], v[168:171], v[96:99]
	v_mfma_f32_16x16x32_bf16 v[84:87], v[136:139], v[176:179], v[84:87]
	v_mfma_f32_16x16x32_bf16 v[80:83], v[144:147], v[176:179], v[80:83]
	s_setprio 0
	s_barrier
	s_add_i32 s65, 0, 0x14000
	s_add_i32 s64, s64, s60
	v_add_u32_e32 v195, s65, v239
	v_mad_u64_u32 v[200:201], s[56:57], s90, v236, v[204:205]
	s_mov_b32 m0, s64
	ds_read_b128 v[180:183], v195
	ds_read_b128 v[184:187], v195 offset:1024
	ds_read_b128 v[188:191], v195 offset:2048
	ds_read_b128 v[210:213], v195 offset:3072
	global_load_lds_dwordx4 v200, s[88:89]
	v_mad_u64_u32 v[202:203], s[56:57], s90, v237, v[206:207]
	s_add_i32 m0, s64, 0x2000
	v_mov_b32_e32 v201, v221
	global_load_lds_dwordx4 v202, s[88:89]
	s_barrier
	s_waitcnt lgkmcnt(0)
	v_mov_b32_e32 v203, v221
	v_lshl_add_u64 v[214:215], s[88:89], 0, v[200:201]
	v_lshl_add_u64 v[216:217], s[88:89], 0, v[202:203]
	s_setprio 1
	s_waitcnt lgkmcnt(0)
	v_mfma_f32_16x16x32_bf16 v[108:111], v[180:183], v[148:151], v[108:111]
	v_mfma_f32_16x16x32_bf16 v[104:107], v[188:191], v[148:151], v[104:107]
	v_mfma_f32_16x16x32_bf16 v[92:95], v[180:183], v[156:159], v[92:95]
	v_mfma_f32_16x16x32_bf16 v[88:91], v[188:191], v[156:159], v[88:91]
	v_mfma_f32_16x16x32_bf16 v[76:79], v[180:183], v[164:167], v[76:79]
	v_mfma_f32_16x16x32_bf16 v[72:75], v[188:191], v[164:167], v[72:75]
	v_mfma_f32_16x16x32_bf16 v[68:71], v[180:183], v[172:175], v[68:71]
	v_mfma_f32_16x16x32_bf16 v[64:67], v[188:191], v[172:175], v[64:67]
	v_mfma_f32_16x16x32_bf16 v[108:111], v[184:187], v[152:155], v[108:111]
	v_mfma_f32_16x16x32_bf16 v[104:107], v[210:213], v[152:155], v[104:107]
	v_mfma_f32_16x16x32_bf16 v[92:95], v[184:187], v[160:163], v[92:95]
	v_mfma_f32_16x16x32_bf16 v[88:91], v[210:213], v[160:163], v[88:91]
	v_mfma_f32_16x16x32_bf16 v[76:79], v[184:187], v[168:171], v[76:79]
	v_mfma_f32_16x16x32_bf16 v[72:75], v[210:213], v[168:171], v[72:75]
	v_mfma_f32_16x16x32_bf16 v[68:71], v[184:187], v[176:179], v[68:71]
	v_mfma_f32_16x16x32_bf16 v[64:67], v[210:213], v[176:179], v[64:67]
	s_setprio 0
	s_mov_b32 m0, s39
	v_mad_u64_u32 v[218:219], s[56:57], vcc_lo, v234, v[204:205]
	s_barrier
	ds_read_b128 v[148:151], v241 offset:16384
	ds_read_b128 v[152:155], v241 offset:17408
	ds_read_b128 v[156:159], v241 offset:18432
	ds_read_b128 v[160:163], v241 offset:19456
	ds_read_b128 v[164:167], v241 offset:20480
	ds_read_b128 v[168:171], v241 offset:21504
	ds_read_b128 v[172:175], v241 offset:22528
	ds_read_b128 v[176:179], v241 offset:23552
	global_load_lds_dwordx4 v218, s[46:47]
	v_mad_u64_u32 v[222:223], s[56:57], vcc_lo, v235, v[206:207]
	s_mov_b32 m0, s38
	v_mov_b32_e32 v219, v221
	global_load_lds_dwordx4 v222, s[46:47]
	s_barrier
	s_waitcnt lgkmcnt(0)
	v_mov_b32_e32 v223, v221
	v_lshl_add_u64 v[242:243], s[46:47], 0, v[218:219]
	v_lshl_add_u64 v[244:245], s[46:47], 0, v[222:223]
	s_setprio 1
	s_waitcnt lgkmcnt(0)
	v_mfma_f32_16x16x32_bf16 v[60:63], v[132:135], v[148:151], v[60:63]
	s_lshl_b64 s[56:57], s[90:91], 7
	v_mfma_f32_16x16x32_bf16 v[56:59], v[140:143], v[148:151], v[56:59]
	v_mfma_f32_16x16x32_bf16 v[52:55], v[132:135], v[156:159], v[52:55]
	v_mfma_f32_16x16x32_bf16 v[48:51], v[140:143], v[156:159], v[48:51]
	v_mfma_f32_16x16x32_bf16 v[36:39], v[132:135], v[164:167], v[36:39]
	v_mfma_f32_16x16x32_bf16 v[32:35], v[140:143], v[164:167], v[32:35]
	v_mfma_f32_16x16x32_bf16 v[20:23], v[132:135], v[172:175], v[20:23]
	v_mfma_f32_16x16x32_bf16 v[16:19], v[140:143], v[172:175], v[16:19]
	v_mfma_f32_16x16x32_bf16 v[60:63], v[136:139], v[152:155], v[60:63]
	v_mfma_f32_16x16x32_bf16 v[56:59], v[144:147], v[152:155], v[56:59]
	v_mfma_f32_16x16x32_bf16 v[52:55], v[136:139], v[160:163], v[52:55]
	v_mfma_f32_16x16x32_bf16 v[48:51], v[144:147], v[160:163], v[48:51]
	v_mfma_f32_16x16x32_bf16 v[36:39], v[136:139], v[168:171], v[36:39]
	v_mfma_f32_16x16x32_bf16 v[32:35], v[144:147], v[168:171], v[32:35]
	v_mfma_f32_16x16x32_bf16 v[20:23], v[136:139], v[176:179], v[20:23]
	v_mfma_f32_16x16x32_bf16 v[16:19], v[144:147], v[176:179], v[16:19]
	s_setprio 0
	s_barrier
; #define PG8_LDA(dst, b, h) do { _Pragma("unroll") for (int m = 0; m < 4; ++m) _Pragma("unroll") for (int k = 0; k < 2; ++k) dst[m][k] = *(const LAS bf16x8*)(lds + PG8_SA(b, h) + aoff + m * 2048 + k * 1024); } while (0)
; #define PG8_LDB(dst, b, h) do { _Pragma("unroll") for (int n = 0; n < 2; ++n) _Pragma("unroll") for (int k = 0; k < 2; ++k) dst[n][k] = *(const LAS bf16x8*)(lds + PG8_SB(b, h) + boff + n * 2048 + k * 1024); } while (0)
; #define PG8_MMA(ai, bj, At, Bt_) do { __builtin_amdgcn_s_setprio(1); _Pragma("unroll") for (int m = 0; m < 4; ++m) _Pragma("unroll") for (int n = 0; n < 2; ++n) _Pragma("unroll") for (int k = 0; k < 2; ++k) \
;     acc[ai][bj][m][n] = __builtin_amdgcn_mfma_f32_16x16x32_bf16(Bt_[n][k], At[m][k], acc[ai][bj][m][n], 0, 0, 0); __builtin_amdgcn_s_setprio(0); } while (0)
; #define PG8_WAIT_V(n) asm volatile("s_waitcnt vmcnt(" #n ")" ::: "memory")
; #define PG8_WAIT_L(n) asm volatile("s_waitcnt lgkmcnt(" #n ")" ::: "memory")
; #define PG8_BAR __builtin_amdgcn_s_barrier()
; #define PG8_SCHED __builtin_amdgcn_sched_barrier(0)
; #define PG8_STA(bufoff, gbase, ld2) PG8_STAGE3(bufoff, gbase, ld2, R0, R1)
; #define PG8_STB(bufoff, gbase, ld2) PG8_STAGE3(bufoff, gbase, ld2, Rb0, Rb1)
; #define PG8_LDA(dst, b, h) do { _Pragma("unroll") for (int m = 0; m < 4; ++m) _Pragma("unroll") for (int k = 0; k < 2; ++k) dst[m][k] = *(const LAS bf16x8*)(lds + PG8_SA(b, h) + aoff + m * 2048 + k * 1024); } while (0)
; #define PG8_LDB(dst, b, h) do { _Pragma("unroll") for (int n = 0; n < 2; ++n) _Pragma("unroll") for (int k = 0; k < 2; ++k) dst[n][k] = *(const LAS bf16x8*)(lds + PG8_SB(b, h) + boff + n * 2048 + k * 1024); } while (0)
; #define PG8_WAIT_V(n) asm volatile("s_waitcnt vmcnt(" #n ")" ::: "memory")
; template <class Sched, class Epi>
; DI void gemm_stream(char* smem, const Sched& S_, const Epi& E) {
;     ...
;       PG8_STB(PG8_SB(0, 1), b2 + xhB, xb2);
;       PG8_WAIT_V(6); PG8_BAR; PG8_MMA(1, 1, At, B1); PG8_BAR;
;       PG8_LDB(B0, 1, 0); PG8_SCHED; PG8_LDA(At, 1, 0); PG8_STA(PG8_SA(0, 1), a2 + xhA, xa2);
;       PG8_WAIT_L(8); PG8_BAR; PG8_WAIT_L(0); PG8_MMA(0, 0, At, B0); PG8_BAR; PG8_SCHED;
;       PG8_LDB(B1, 1, 1); PG8_STB(PG8_SB(1, 0), b3, xb2);
;       PG8_BAR; PG8_WAIT_L(0); PG8_MMA(0, 1, At, B1); PG8_BAR;
;       PG8_LDA(At, 1, 1); PG8_STA(PG8_SA(1, 0), a3, xa2);
;       PG8_BAR; PG8_WAIT_L(0); PG8_MMA(1, 0, At, B0); PG8_BAR; PG8_SCHED;
	s_add_u32 s56, s88, s56
	s_addc_u32 s57, s89, s57
	s_add_i32 s64, s65, s60
	s_mov_b32 m0, s64
	s_nop 0
	global_load_lds_dwordx4 v200, s[56:57]
	s_add_i32 m0, s64, 0x2000
	v_lshl_add_u64 v[200:201], s[56:57], 0, v[200:201]
	global_load_lds_dwordx4 v202, s[56:57]
	s_waitcnt vmcnt(6)
	v_lshl_add_u64 v[202:203], s[56:57], 0, v[202:203]
	s_barrier
	s_setprio 1
	v_mfma_f32_16x16x32_bf16 v[44:47], v[180:183], v[148:151], v[44:47]
	v_mfma_f32_16x16x32_bf16 v[40:43], v[188:191], v[148:151], v[40:43]
	v_mfma_f32_16x16x32_bf16 v[28:31], v[180:183], v[156:159], v[28:31]
	v_mfma_f32_16x16x32_bf16 v[24:27], v[188:191], v[156:159], v[24:27]
	v_mfma_f32_16x16x32_bf16 v[12:15], v[180:183], v[164:167], v[12:15]
	v_mfma_f32_16x16x32_bf16 v[8:11], v[188:191], v[164:167], v[8:11]
	v_mfma_f32_16x16x32_bf16 v[4:7], v[180:183], v[172:175], v[4:7]
	v_mfma_f32_16x16x32_bf16 v[0:3], v[188:191], v[172:175], v[0:3]
	v_mfma_f32_16x16x32_bf16 v[44:47], v[184:187], v[152:155], v[44:47]
	v_mfma_f32_16x16x32_bf16 v[40:43], v[210:213], v[152:155], v[40:43]
	v_mfma_f32_16x16x32_bf16 v[28:31], v[184:187], v[160:163], v[28:31]
	v_mfma_f32_16x16x32_bf16 v[24:27], v[210:213], v[160:163], v[24:27]
	v_mfma_f32_16x16x32_bf16 v[12:15], v[184:187], v[168:171], v[12:15]
	v_mfma_f32_16x16x32_bf16 v[8:11], v[210:213], v[168:171], v[8:11]
	v_mfma_f32_16x16x32_bf16 v[4:7], v[184:187], v[176:179], v[4:7]
	v_mfma_f32_16x16x32_bf16 v[0:3], v[210:213], v[176:179], v[0:3]
	s_setprio 0
	s_add_i32 s56, 0, 0x18000
	v_add_u32_e32 v144, s56, v239
	s_barrier
	ds_read_b128 v[132:135], v144
	ds_read_b128 v[136:139], v144 offset:1024
	ds_read_b128 v[140:143], v144 offset:2048
	ds_read_b128 v[144:147], v144 offset:3072
	s_add_u32 s46, s46, s50
	s_addc_u32 s47, s47, s51
	s_mov_b32 m0, s9
	ds_read_b128 v[148:151], v241 offset:32768
	ds_read_b128 v[152:155], v241 offset:33792
	ds_read_b128 v[156:159], v241 offset:34816
	ds_read_b128 v[160:163], v241 offset:35840
	ds_read_b128 v[164:167], v241 offset:36864
	ds_read_b128 v[168:171], v241 offset:37888
	ds_read_b128 v[172:175], v241 offset:38912
	ds_read_b128 v[176:179], v241 offset:39936
	global_load_lds_dwordx4 v218, s[46:47]
	s_mov_b32 m0, s26
	s_nop 0
	global_load_lds_dwordx4 v222, s[46:47]
	s_waitcnt lgkmcnt(8)
	s_barrier
	s_waitcnt lgkmcnt(0)
	s_setprio 1
	s_waitcnt lgkmcnt(0)
	v_mfma_f32_16x16x32_bf16 v[124:127], v[132:135], v[148:151], v[124:127]
	v_mfma_f32_16x16x32_bf16 v[120:123], v[140:143], v[148:151], v[120:123]
	v_mfma_f32_16x16x32_bf16 v[116:119], v[132:135], v[156:159], v[116:119]
	v_mfma_f32_16x16x32_bf16 v[112:115], v[140:143], v[156:159], v[112:115]
	v_mfma_f32_16x16x32_bf16 v[100:103], v[132:135], v[164:167], v[100:103]
	v_mfma_f32_16x16x32_bf16 v[96:99], v[140:143], v[164:167], v[96:99]
	v_mfma_f32_16x16x32_bf16 v[84:87], v[132:135], v[172:175], v[84:87]
	v_mfma_f32_16x16x32_bf16 v[80:83], v[140:143], v[172:175], v[80:83]
	v_mfma_f32_16x16x32_bf16 v[124:127], v[136:139], v[152:155], v[124:127]
	v_mfma_f32_16x16x32_bf16 v[120:123], v[144:147], v[152:155], v[120:123]
	v_mfma_f32_16x16x32_bf16 v[116:119], v[136:139], v[160:163], v[116:119]
	v_mfma_f32_16x16x32_bf16 v[112:115], v[144:147], v[160:163], v[112:115]
	v_mfma_f32_16x16x32_bf16 v[100:103], v[136:139], v[168:171], v[100:103]
	v_mfma_f32_16x16x32_bf16 v[96:99], v[144:147], v[168:171], v[96:99]
	v_mfma_f32_16x16x32_bf16 v[84:87], v[136:139], v[176:179], v[84:87]
	v_mfma_f32_16x16x32_bf16 v[80:83], v[144:147], v[176:179], v[80:83]
	s_setprio 0
	s_barrier
	s_add_i32 s46, 0, 0x1c000
	s_add_i32 s47, s56, s60
	v_add_u32_e32 v195, s46, v239
	v_lshl_add_u64 v[214:215], v[214:215], 0, s[58:59]
	s_mov_b32 m0, s47
	ds_read_b128 v[180:183], v195
	ds_read_b128 v[184:187], v195 offset:1024
	ds_read_b128 v[188:191], v195 offset:2048
	ds_read_b128 v[210:213], v195 offset:3072
	global_load_lds_dwordx4 v[214:215], off
	v_lshl_add_u64 v[214:215], v[216:217], 0, s[58:59]
	s_add_i32 m0, s47, 0x2000
	s_nop 0
	global_load_lds_dwordx4 v[214:215], off
	s_barrier
	s_waitcnt lgkmcnt(0)
	s_setprio 1
	s_waitcnt lgkmcnt(0)
	v_mfma_f32_16x16x32_bf16 v[108:111], v[180:183], v[148:151], v[108:111]
	v_mfma_f32_16x16x32_bf16 v[104:107], v[188:191], v[148:151], v[104:107]
	v_mfma_f32_16x16x32_bf16 v[92:95], v[180:183], v[156:159], v[92:95]
	v_mfma_f32_16x16x32_bf16 v[88:91], v[188:191], v[156:159], v[88:91]
	v_mfma_f32_16x16x32_bf16 v[76:79], v[180:183], v[164:167], v[76:79]
	v_mfma_f32_16x16x32_bf16 v[72:75], v[188:191], v[164:167], v[72:75]
	v_mfma_f32_16x16x32_bf16 v[68:71], v[180:183], v[172:175], v[68:71]
	v_mfma_f32_16x16x32_bf16 v[64:67], v[188:191], v[172:175], v[64:67]
	v_mfma_f32_16x16x32_bf16 v[108:111], v[184:187], v[152:155], v[108:111]
	v_mfma_f32_16x16x32_bf16 v[104:107], v[210:213], v[152:155], v[104:107]
	v_mfma_f32_16x16x32_bf16 v[92:95], v[184:187], v[160:163], v[92:95]
	v_mfma_f32_16x16x32_bf16 v[88:91], v[210:213], v[160:163], v[88:91]
	v_mfma_f32_16x16x32_bf16 v[76:79], v[184:187], v[168:171], v[76:79]
	v_mfma_f32_16x16x32_bf16 v[72:75], v[210:213], v[168:171], v[72:75]
	v_mfma_f32_16x16x32_bf16 v[68:71], v[184:187], v[176:179], v[68:71]
	v_mfma_f32_16x16x32_bf16 v[64:67], v[210:213], v[176:179], v[64:67]
	s_setprio 0
	s_mov_b32 m0, s27
	v_lshl_add_u64 v[214:215], v[242:243], 0, s[58:59]
	s_barrier
	ds_read_b128 v[148:151], v241 offset:49152
	ds_read_b128 v[152:155], v241 offset:50176
	ds_read_b128 v[156:159], v241 offset:51200
	ds_read_b128 v[160:163], v241 offset:52224
	ds_read_b128 v[164:167], v241 offset:53248
	ds_read_b128 v[168:171], v241 offset:54272
	ds_read_b128 v[172:175], v241 offset:55296
	ds_read_b128 v[176:179], v241 offset:56320
	global_load_lds_dwordx4 v[214:215], off
	v_lshl_add_u64 v[214:215], v[244:245], 0, s[58:59]
	s_mov_b32 m0, s33
	s_nop 0
	global_load_lds_dwordx4 v[214:215], off
	s_barrier
; DI int get_tid() { int t = threadIdx.x; asm volatile("" : "+v"(t)); return t; }
; #define MEMBAR() asm volatile("" ::: "memory")
; #define PG8_MMA(ai, bj, At, Bt_) do { __builtin_amdgcn_s_setprio(1); _Pragma("unroll") for (int m = 0; m < 4; ++m) _Pragma("unroll") for (int n = 0; n < 2; ++n) _Pragma("unroll") for (int k = 0; k < 2; ++k) \
;     acc[ai][bj][m][n] = __builtin_amdgcn_mfma_f32_16x16x32_bf16(Bt_[n][k], At[m][k], acc[ai][bj][m][n], 0, 0, 0); __builtin_amdgcn_s_setprio(0); } while (0)
; #define PG8_WAIT_V(n) asm volatile("s_waitcnt vmcnt(" #n ")" ::: "memory")
; #define PG8_BAR __builtin_amdgcn_s_barrier()
; DI u32x4 pack8v(const f32x4& a, const f32x4& b) { u32x4 w; w.x = pk2(a[0], a[1]); w.y = pk2(a[2], a[3]); w.z = pk2(b[0], b[1]); w.w = pk2(b[2], b[3]); return w; }
; #define PG8_STB(bufoff, gbase, ld2) PG8_STAGE3(bufoff, gbase, ld2, Rb0, Rb1)
; #define PG8_WAIT_V(n) asm volatile("s_waitcnt vmcnt(" #n ")" ::: "memory")
; #define PG8_BAR __builtin_amdgcn_s_barrier()
; template <class Sched, class Epi>
; DI void gemm_stream(char* smem, const Sched& S_, const Epi& E) {
;     ...
;       PG8_STB(PG8_SB(1, 1), b3 + xhB, xb2);
;       PG8_WAIT_V(6); PG8_BAR; PG8_MMA(1, 1, At, B1); PG8_BAR;
;     }
;   DI void operator()(const acc_t& acc, const Desc& u, int wr, int wc, int fr, int fq) const {
;     u32x4* sp = slab + get_tid(); asm volatile("" : "+v"(sp));
;     if (!(u.kind & 1)) {
; #pragma unroll
;       for (int ai = 0; ai < 2; ++ai)
; #pragma unroll
;         for (int m = 0; m < 4; ++m)
; #pragma unroll
;           for (int bj = 0; bj < 2; ++bj) sp[((ai * 4 + m) * 2 + bj) * 512] = pack8v(acc[ai][bj][m][0], acc[ai][bj][m][1]);
;     } else {
;       const int first = u.kind == 1, lastx = u.kind == 5;
;       const int row0 = u.pm * BM + wr * 64 + fr, col0 = u.pn * BM + wc * 32 + 8 * fq;
; #pragma unroll
;       for (int ai = 0; ai < 2; ++ai) {
;         MEMBAR();
;         u32x4 pv[4][2], mv[4][2];
; #pragma unroll
;         for (int m = 0; m < 4; ++m)
; #pragma unroll
;           for (int bj = 0; bj < 2; ++bj) {
;             pv[m][bj] = sp[((ai * 4 + m) * 2 + bj) * 512];
;             if (!first) mv[m][bj] = sp[(16 + (ai * 4 + m) * 2 + bj) * 512];
;           }
	s_waitcnt lgkmcnt(0)
	s_setprio 1
	s_waitcnt lgkmcnt(0)
	v_mfma_f32_16x16x32_bf16 v[60:63], v[132:135], v[148:151], v[60:63]
	v_mfma_f32_16x16x32_bf16 v[56:59], v[140:143], v[148:151], v[56:59]
	v_mfma_f32_16x16x32_bf16 v[52:55], v[132:135], v[156:159], v[52:55]
	v_mfma_f32_16x16x32_bf16 v[48:51], v[140:143], v[156:159], v[48:51]
	v_mfma_f32_16x16x32_bf16 v[36:39], v[132:135], v[164:167], v[36:39]
	v_mfma_f32_16x16x32_bf16 v[32:35], v[140:143], v[164:167], v[32:35]
	v_mfma_f32_16x16x32_bf16 v[20:23], v[132:135], v[172:175], v[20:23]
	v_mfma_f32_16x16x32_bf16 v[16:19], v[140:143], v[172:175], v[16:19]
	v_mfma_f32_16x16x32_bf16 v[60:63], v[136:139], v[152:155], v[60:63]
	v_mfma_f32_16x16x32_bf16 v[56:59], v[144:147], v[152:155], v[56:59]
	v_mfma_f32_16x16x32_bf16 v[52:55], v[136:139], v[160:163], v[52:55]
	v_mfma_f32_16x16x32_bf16 v[48:51], v[144:147], v[160:163], v[48:51]
	v_mfma_f32_16x16x32_bf16 v[36:39], v[136:139], v[168:171], v[36:39]
	v_mfma_f32_16x16x32_bf16 v[32:35], v[144:147], v[168:171], v[32:35]
	v_mfma_f32_16x16x32_bf16 v[20:23], v[136:139], v[176:179], v[20:23]
	v_mfma_f32_16x16x32_bf16 v[16:19], v[144:147], v[176:179], v[16:19]
	s_setprio 0
	s_barrier
	s_add_i32 s46, s46, s60
	v_lshl_add_u64 v[132:133], v[200:201], 0, s[58:59]
	s_mov_b32 m0, s46
	s_nop 0
	global_load_lds_dwordx4 v[132:133], off
	v_lshl_add_u64 v[132:133], v[202:203], 0, s[58:59]
	s_add_i32 m0, s46, 0x2000
	s_nop 0
	global_load_lds_dwordx4 v[132:133], off
	s_waitcnt vmcnt(6)
	s_barrier
	s_setprio 1
	v_mfma_f32_16x16x32_bf16 v[44:47], v[180:183], v[148:151], v[44:47]
	v_mfma_f32_16x16x32_bf16 v[40:43], v[188:191], v[148:151], v[40:43]
	v_mfma_f32_16x16x32_bf16 v[28:31], v[180:183], v[156:159], v[28:31]
	v_mfma_f32_16x16x32_bf16 v[24:27], v[188:191], v[156:159], v[24:27]
	v_mfma_f32_16x16x32_bf16 v[12:15], v[180:183], v[164:167], v[12:15]
	v_mfma_f32_16x16x32_bf16 v[8:11], v[188:191], v[164:167], v[8:11]
	v_mfma_f32_16x16x32_bf16 v[4:7], v[180:183], v[172:175], v[4:7]
	v_mfma_f32_16x16x32_bf16 v[0:3], v[188:191], v[172:175], v[0:3]
	v_mfma_f32_16x16x32_bf16 v[44:47], v[184:187], v[152:155], v[44:47]
	v_mfma_f32_16x16x32_bf16 v[40:43], v[210:213], v[152:155], v[40:43]
	v_mfma_f32_16x16x32_bf16 v[28:31], v[184:187], v[160:163], v[28:31]
	v_mfma_f32_16x16x32_bf16 v[24:27], v[210:213], v[160:163], v[24:27]
	v_mfma_f32_16x16x32_bf16 v[12:15], v[184:187], v[168:171], v[12:15]
	v_mfma_f32_16x16x32_bf16 v[8:11], v[210:213], v[168:171], v[8:11]
	v_mfma_f32_16x16x32_bf16 v[4:7], v[184:187], v[176:179], v[4:7]
	v_mfma_f32_16x16x32_bf16 v[0:3], v[210:213], v[176:179], v[0:3]
	s_setprio 0
	s_add_u32 s44, s44, 0x100
	s_addc_u32 s45, s45, 0
	s_add_u32 s63, s63, 0x100
	s_addc_u32 s52, s52, 0
	s_cmp_ge_i32 s53, s5
	s_mov_b32 s46, s53
	s_barrier
	s_cbranch_scc0 .LBB0_1166
	v_mov_b32_e32 v128, v192
	v_readlane_b32 s44, v252, 45
	s_bitcmp1_b32 s4, 0
	v_readlane_b32 s45, v252, 46
	v_ashrrev_i32_e32 v129, 31, v128
	s_cselect_b64 s[46:47], -1, 0
	v_readlane_b32 s62, v254, 39
	v_readlane_b32 s88, v254, 43
	v_lshl_add_u64 v[210:211], v[128:129], 4, s[44:45]
	s_mov_b64 s[44:45], -1
	s_and_b64 vcc, exec, s[46:47]
	v_readlane_b32 s63, v254, 40
	v_readlane_b32 s89, v254, 44
	v_readlane_b32 s53, v253, 4
	s_movk_i32 s80, 0xef00
	s_cbranch_vccz .LBB0_1297
	global_load_dwordx4 v[188:191], v[210:211], off
	s_cmp_lg_u32 s4, 1
	s_cselect_b64 s[46:47], -1, 0
	s_cmp_eq_u32 s4, 1
	s_cbranch_scc1 .LBB0_1170
	v_add_co_u32_e32 v128, vcc, 0x20000, v210
	s_nop 1
	v_addc_co_u32_e32 v129, vcc, 0, v211, vcc
	global_load_dwordx4 v[156:159], v[128:129], off
.LBB0_1170:
	v_add_co_u32_e32 v128, vcc, 0x2000, v210
	s_nop 1
	v_addc_co_u32_e32 v129, vcc, 0, v211, vcc
	global_load_dwordx4 v[184:187], v[128:129], off
	v_cndmask_b32_e64 v128, 0, 1, s[46:47]
	v_cmp_ne_u32_e64 s[44:45], 1, v128
	s_andn2_b64 vcc, exec, s[46:47]
	s_cbranch_vccnz .LBB0_1172
	v_add_co_u32_e32 v128, vcc, 0x22000, v210
	s_nop 1
	v_addc_co_u32_e32 v129, vcc, 0, v211, vcc
	global_load_dwordx4 v[152:155], v[128:129], off
.LBB0_1172:
	v_add_co_u32_e32 v128, vcc, 0x4000, v210
	s_nop 1
	v_addc_co_u32_e32 v129, vcc, 0, v211, vcc
	global_load_dwordx4 v[180:183], v[128:129], off
	s_and_b64 vcc, exec, s[44:45]
	s_cbranch_vccnz .LBB0_1174
	v_add_co_u32_e32 v128, vcc, 0x24000, v210
	s_nop 1
	v_addc_co_u32_e32 v129, vcc, 0, v211, vcc
	global_load_dwordx4 v[148:151], v[128:129], off
.LBB0_1174:
	v_add_co_u32_e32 v128, vcc, 0x6000, v210
	s_nop 1
	v_addc_co_u32_e32 v129, vcc, 0, v211, vcc
	global_load_dwordx4 v[176:179], v[128:129], off
	s_and_b64 vcc, exec, s[44:45]
	s_cbranch_vccnz .LBB0_1176
	v_add_co_u32_e32 v128, vcc, 0x26000, v210
	s_nop 1
	v_addc_co_u32_e32 v129, vcc, 0, v211, vcc
	global_load_dwordx4 v[144:147], v[128:129], off
.LBB0_1176:
	v_add_co_u32_e32 v128, vcc, 0x8000, v210
	s_nop 1
	v_addc_co_u32_e32 v129, vcc, 0, v211, vcc
	global_load_dwordx4 v[172:175], v[128:129], off
	s_and_b64 vcc, exec, s[44:45]
	s_cbranch_vccnz .LBB0_1178
	v_add_co_u32_e32 v128, vcc, 0x28000, v210
	s_nop 1
	v_addc_co_u32_e32 v129, vcc, 0, v211, vcc
	global_load_dwordx4 v[140:143], v[128:129], off
.LBB0_1178:
	v_add_co_u32_e32 v128, vcc, 0xa000, v210
	s_nop 1
	v_addc_co_u32_e32 v129, vcc, 0, v211, vcc
	global_load_dwordx4 v[168:171], v[128:129], off
	s_and_b64 vcc, exec, s[44:45]
	s_cbranch_vccnz .LBB0_1180
	v_add_co_u32_e32 v128, vcc, 0x2a000, v210
	s_nop 1
	v_addc_co_u32_e32 v129, vcc, 0, v211, vcc
	global_load_dwordx4 v[136:139], v[128:129], off
.LBB0_1180:
	v_add_co_u32_e32 v128, vcc, 0xc000, v210
	s_nop 1
	v_addc_co_u32_e32 v129, vcc, 0, v211, vcc
	global_load_dwordx4 v[164:167], v[128:129], off
	s_and_b64 vcc, exec, s[44:45]
	s_cbranch_vccnz .LBB0_1182
	v_add_co_u32_e32 v128, vcc, 0x2c000, v210
	s_nop 1
	v_addc_co_u32_e32 v129, vcc, 0, v211, vcc
	global_load_dwordx4 v[132:135], v[128:129], off
.LBB0_1182:
	v_add_co_u32_e32 v128, vcc, 0xe000, v210
	s_nop 1
	v_addc_co_u32_e32 v129, vcc, 0, v211, vcc
	global_load_dwordx4 v[160:163], v[128:129], off
	s_and_b64 vcc, exec, s[44:45]
	s_cbranch_vccnz .LBB0_1184
	v_add_co_u32_e32 v128, vcc, 0x2e000, v210
	s_nop 1
	v_addc_co_u32_e32 v129, vcc, 0, v211, vcc
	global_load_dwordx4 v[128:131], v[128:129], off

; DI float bflo(unsigned u) { return __uint_as_float(u << 16); }
; DI float bfhi(unsigned u) { return __uint_as_float(u & 0xffff0000u); }
; DI float sigmoidf_(float x) { return __builtin_amdgcn_rcpf(1.f + __builtin_amdgcn_exp2f(-1.4426950408889634f * x)); }
; DI u32x4 pack8v(const f32x4& a, const f32x4& b) { u32x4 w; w.x = pk2(a[0], a[1]); w.y = pk2(a[2], a[3]); w.z = pk2(b[0], b[1]); w.w = pk2(b[2], b[3]); return w; }
;   DI void operator()(const acc_t& acc, const Desc& u, int wr, int wc, int fr, int fq) const {
;     ...
;           for (int bj = 0; bj < 2; ++bj) {
;             const u32x4 pq = pv[m][bj];
;             f32x4 r0, r1;
;             const f32x4& g0 = acc[ai][bj][m][0]; const f32x4& g1 = acc[ai][bj][m][1];
;             r0[0] = sigmoidf_(g0[0]) * bflo(pq.x); r0[1] = sigmoidf_(g0[1]) * bfhi(pq.x); r0[2] = sigmoidf_(g0[2]) * bflo(pq.y); r0[3] = sigmoidf_(g0[3]) * bfhi(pq.y);
;             r1[0] = sigmoidf_(g1[0]) * bflo(pq.z); r1[1] = sigmoidf_(g1[1]) * bfhi(pq.z); r1[2] = sigmoidf_(g1[2]) * bflo(pq.w); r1[3] = sigmoidf_(g1[3]) * bfhi(pq.w);
;             if (!first) { const u32x4 mq = mv[m][bj];
;               r0[0] += bflo(mq.x); r0[1] += bfhi(mq.x); r0[2] += bflo(mq.y); r0[3] += bfhi(mq.y); r1[0] += bflo(mq.z); r1[1] += bfhi(mq.z); r1[2] += bflo(mq.w); r1[3] += bfhi(mq.w); }
;             const u32x4 res = pack8v(r0, r1);
;             if (lastx) *(u32x4*)(M + (size_t)(row0 + ai * HALF + m * 16) * ZS + col0 + bj * HALF) = res;
;             else sp[(16 + (ai * 4 + m) * 2 + bj) * 512] = res;
.LBB0_1186:
	s_cmp_lg_u32 s4, 5
	s_cselect_b64 s[50:51], -1, 0
	v_cvt_pk_bf16_f32 v188, v212, v213
	v_cvt_pk_bf16_f32 v189, v214, v215
	v_cvt_pk_bf16_f32 v190, v216, v217
	v_cvt_pk_bf16_f32 v191, v218, v219
	s_mov_b64 s[46:47], -1
	s_and_b64 vcc, exec, s[50:51]
	s_cbranch_vccz .LBB0_1188
	v_add_co_u32_e32 v200, vcc, 0x20000, v210
	s_mov_b64 s[46:47], 0
	s_nop 0
	v_addc_co_u32_e32 v201, vcc, 0, v211, vcc
	global_store_dwordx4 v[200:201], v[188:191], off

; DI float bflo(unsigned u) { return __uint_as_float(u << 16); }
; DI float bfhi(unsigned u) { return __uint_as_float(u & 0xffff0000u); }
; DI float sigmoidf_(float x) { return __builtin_amdgcn_rcpf(1.f + __builtin_amdgcn_exp2f(-1.4426950408889634f * x)); }
; DI u32x4 pack8v(const f32x4& a, const f32x4& b) { u32x4 w; w.x = pk2(a[0], a[1]); w.y = pk2(a[2], a[3]); w.z = pk2(b[0], b[1]); w.w = pk2(b[2], b[3]); return w; }
;   DI void operator()(const acc_t& acc, const Desc& u, int wr, int wc, int fr, int fq) const {
;     ...
;           for (int bj = 0; bj < 2; ++bj) {
;             const u32x4 pq = pv[m][bj];
;             f32x4 r0, r1;
;             const f32x4& g0 = acc[ai][bj][m][0]; const f32x4& g1 = acc[ai][bj][m][1];
;             r0[0] = sigmoidf_(g0[0]) * bflo(pq.x); r0[1] = sigmoidf_(g0[1]) * bfhi(pq.x); r0[2] = sigmoidf_(g0[2]) * bflo(pq.y); r0[3] = sigmoidf_(g0[3]) * bfhi(pq.y);
;             r1[0] = sigmoidf_(g1[0]) * bflo(pq.z); r1[1] = sigmoidf_(g1[1]) * bfhi(pq.z); r1[2] = sigmoidf_(g1[2]) * bflo(pq.w); r1[3] = sigmoidf_(g1[3]) * bfhi(pq.w);
;             if (!first) { const u32x4 mq = mv[m][bj];
;               r0[0] += bflo(mq.x); r0[1] += bfhi(mq.x); r0[2] += bflo(mq.y); r0[3] += bfhi(mq.y); r1[0] += bflo(mq.z); r1[1] += bfhi(mq.z); r1[2] += bflo(mq.w); r1[3] += bfhi(mq.w); }
;             const u32x4 res = pack8v(r0, r1);
;             if (lastx) *(u32x4*)(M + (size_t)(row0 + ai * HALF + m * 16) * ZS + col0 + bj * HALF) = res;
;             else sp[(16 + (ai * 4 + m) * 2 + bj) * 512] = res;
.LBB0_1192:
	v_cvt_pk_bf16_f32 v184, v188, v189
	v_cndmask_b32_e64 v188, 0, 1, s[50:51]
	v_cvt_pk_bf16_f32 v185, v190, v191
	v_cvt_pk_bf16_f32 v186, v216, v217
	v_cvt_pk_bf16_f32 v187, v218, v219
	v_cmp_ne_u32_e64 s[46:47], 1, v188
	s_andn2_b64 vcc, exec, s[50:51]
	s_mov_b64 s[50:51], -1
	s_cbranch_vccnz .LBB0_1194
	v_add_co_u32_e32 v188, vcc, 0x22000, v210
	s_mov_b64 s[50:51], 0
	s_nop 0
	v_addc_co_u32_e32 v189, vcc, 0, v211, vcc
	global_store_dwordx4 v[188:189], v[184:187], off

; DI float bflo(unsigned u) { return __uint_as_float(u << 16); }
; DI float bfhi(unsigned u) { return __uint_as_float(u & 0xffff0000u); }
; DI float sigmoidf_(float x) { return __builtin_amdgcn_rcpf(1.f + __builtin_amdgcn_exp2f(-1.4426950408889634f * x)); }
; DI u32x4 pack8v(const f32x4& a, const f32x4& b) { u32x4 w; w.x = pk2(a[0], a[1]); w.y = pk2(a[2], a[3]); w.z = pk2(b[0], b[1]); w.w = pk2(b[2], b[3]); return w; }
;   DI void operator()(const acc_t& acc, const Desc& u, int wr, int wc, int fr, int fq) const {
;     ...
;           for (int bj = 0; bj < 2; ++bj) {
;             const u32x4 pq = pv[m][bj];
;             f32x4 r0, r1;
;             const f32x4& g0 = acc[ai][bj][m][0]; const f32x4& g1 = acc[ai][bj][m][1];
;             r0[0] = sigmoidf_(g0[0]) * bflo(pq.x); r0[1] = sigmoidf_(g0[1]) * bfhi(pq.x); r0[2] = sigmoidf_(g0[2]) * bflo(pq.y); r0[3] = sigmoidf_(g0[3]) * bfhi(pq.y);
;             r1[0] = sigmoidf_(g1[0]) * bflo(pq.z); r1[1] = sigmoidf_(g1[1]) * bfhi(pq.z); r1[2] = sigmoidf_(g1[2]) * bflo(pq.w); r1[3] = sigmoidf_(g1[3]) * bfhi(pq.w);
;             if (!first) { const u32x4 mq = mv[m][bj];
;               r0[0] += bflo(mq.x); r0[1] += bfhi(mq.x); r0[2] += bflo(mq.y); r0[3] += bfhi(mq.y); r1[0] += bflo(mq.z); r1[1] += bfhi(mq.z); r1[2] += bflo(mq.w); r1[3] += bfhi(mq.w); }
;             const u32x4 res = pack8v(r0, r1);
;             if (lastx) *(u32x4*)(M + (size_t)(row0 + ai * HALF + m * 16) * ZS + col0 + bj * HALF) = res;
;             else sp[(16 + (ai * 4 + m) * 2 + bj) * 512] = res;
.LBB0_1198:
	v_cvt_pk_bf16_f32 v180, v184, v185
	v_cvt_pk_bf16_f32 v181, v186, v187
	v_cvt_pk_bf16_f32 v182, v188, v189
	v_cvt_pk_bf16_f32 v183, v190, v191
	s_and_b64 vcc, exec, s[46:47]
	s_mov_b64 s[50:51], -1
	s_cbranch_vccnz .LBB0_1200
	v_add_co_u32_e32 v184, vcc, 0x24000, v210
	s_mov_b64 s[50:51], 0
	s_nop 0
	v_addc_co_u32_e32 v185, vcc, 0, v211, vcc
	global_store_dwordx4 v[184:185], v[180:183], off

; DI float bflo(unsigned u) { return __uint_as_float(u << 16); }
; DI float bfhi(unsigned u) { return __uint_as_float(u & 0xffff0000u); }
; DI float sigmoidf_(float x) { return __builtin_amdgcn_rcpf(1.f + __builtin_amdgcn_exp2f(-1.4426950408889634f * x)); }
; DI u32x4 pack8v(const f32x4& a, const f32x4& b) { u32x4 w; w.x = pk2(a[0], a[1]); w.y = pk2(a[2], a[3]); w.z = pk2(b[0], b[1]); w.w = pk2(b[2], b[3]); return w; }
;   DI void operator()(const acc_t& acc, const Desc& u, int wr, int wc, int fr, int fq) const {
;     ...
;           for (int bj = 0; bj < 2; ++bj) {
;             const u32x4 pq = pv[m][bj];
;             f32x4 r0, r1;
;             const f32x4& g0 = acc[ai][bj][m][0]; const f32x4& g1 = acc[ai][bj][m][1];
;             r0[0] = sigmoidf_(g0[0]) * bflo(pq.x); r0[1] = sigmoidf_(g0[1]) * bfhi(pq.x); r0[2] = sigmoidf_(g0[2]) * bflo(pq.y); r0[3] = sigmoidf_(g0[3]) * bfhi(pq.y);
;             r1[0] = sigmoidf_(g1[0]) * bflo(pq.z); r1[1] = sigmoidf_(g1[1]) * bfhi(pq.z); r1[2] = sigmoidf_(g1[2]) * bflo(pq.w); r1[3] = sigmoidf_(g1[3]) * bfhi(pq.w);
;             if (!first) { const u32x4 mq = mv[m][bj];
;               r0[0] += bflo(mq.x); r0[1] += bfhi(mq.x); r0[2] += bflo(mq.y); r0[3] += bfhi(mq.y); r1[0] += bflo(mq.z); r1[1] += bfhi(mq.z); r1[2] += bflo(mq.w); r1[3] += bfhi(mq.w); }
;             const u32x4 res = pack8v(r0, r1);
;             if (lastx) *(u32x4*)(M + (size_t)(row0 + ai * HALF + m * 16) * ZS + col0 + bj * HALF) = res;
;             else sp[(16 + (ai * 4 + m) * 2 + bj) * 512] = res;
.LBB0_1204:
	v_cvt_pk_bf16_f32 v176, v180, v181
	v_cvt_pk_bf16_f32 v177, v182, v183
	v_cvt_pk_bf16_f32 v178, v186, v187
	v_cvt_pk_bf16_f32 v179, v188, v189
	s_and_b64 vcc, exec, s[46:47]
	s_mov_b64 s[50:51], -1
	s_cbranch_vccnz .LBB0_1206
	v_add_co_u32_e32 v180, vcc, 0x26000, v210
	s_mov_b64 s[50:51], 0
	s_nop 0
	v_addc_co_u32_e32 v181, vcc, 0, v211, vcc
	global_store_dwordx4 v[180:181], v[176:179], off

; DI float bflo(unsigned u) { return __uint_as_float(u << 16); }
; DI float bfhi(unsigned u) { return __uint_as_float(u & 0xffff0000u); }
; DI float sigmoidf_(float x) { return __builtin_amdgcn_rcpf(1.f + __builtin_amdgcn_exp2f(-1.4426950408889634f * x)); }
; DI u32x4 pack8v(const f32x4& a, const f32x4& b) { u32x4 w; w.x = pk2(a[0], a[1]); w.y = pk2(a[2], a[3]); w.z = pk2(b[0], b[1]); w.w = pk2(b[2], b[3]); return w; }
;   DI void operator()(const acc_t& acc, const Desc& u, int wr, int wc, int fr, int fq) const {
;     ...
;           for (int bj = 0; bj < 2; ++bj) {
;             const u32x4 pq = pv[m][bj];
;             f32x4 r0, r1;
;             const f32x4& g0 = acc[ai][bj][m][0]; const f32x4& g1 = acc[ai][bj][m][1];
;             r0[0] = sigmoidf_(g0[0]) * bflo(pq.x); r0[1] = sigmoidf_(g0[1]) * bfhi(pq.x); r0[2] = sigmoidf_(g0[2]) * bflo(pq.y); r0[3] = sigmoidf_(g0[3]) * bfhi(pq.y);
;             r1[0] = sigmoidf_(g1[0]) * bflo(pq.z); r1[1] = sigmoidf_(g1[1]) * bfhi(pq.z); r1[2] = sigmoidf_(g1[2]) * bflo(pq.w); r1[3] = sigmoidf_(g1[3]) * bfhi(pq.w);
;             if (!first) { const u32x4 mq = mv[m][bj];
;               r0[0] += bflo(mq.x); r0[1] += bfhi(mq.x); r0[2] += bflo(mq.y); r0[3] += bfhi(mq.y); r1[0] += bflo(mq.z); r1[1] += bfhi(mq.z); r1[2] += bflo(mq.w); r1[3] += bfhi(mq.w); }
;             const u32x4 res = pack8v(r0, r1);
;             if (lastx) *(u32x4*)(M + (size_t)(row0 + ai * HALF + m * 16) * ZS + col0 + bj * HALF) = res;
;             else sp[(16 + (ai * 4 + m) * 2 + bj) * 512] = res;
.LBB0_1210:
	v_cvt_pk_bf16_f32 v172, v176, v177
	v_cvt_pk_bf16_f32 v173, v178, v179
	v_cvt_pk_bf16_f32 v174, v180, v181
	v_cvt_pk_bf16_f32 v175, v182, v183
	s_and_b64 vcc, exec, s[46:47]
	s_mov_b64 s[50:51], -1
	s_cbranch_vccnz .LBB0_1212
	v_add_co_u32_e32 v176, vcc, 0x28000, v210
	s_mov_b64 s[50:51], 0
	s_nop 0
	v_addc_co_u32_e32 v177, vcc, 0, v211, vcc
	global_store_dwordx4 v[176:177], v[172:175], off

; DI float bflo(unsigned u) { return __uint_as_float(u << 16); }
; DI float bfhi(unsigned u) { return __uint_as_float(u & 0xffff0000u); }
; DI float sigmoidf_(float x) { return __builtin_amdgcn_rcpf(1.f + __builtin_amdgcn_exp2f(-1.4426950408889634f * x)); }
; DI u32x4 pack8v(const f32x4& a, const f32x4& b) { u32x4 w; w.x = pk2(a[0], a[1]); w.y = pk2(a[2], a[3]); w.z = pk2(b[0], b[1]); w.w = pk2(b[2], b[3]); return w; }
;   DI void operator()(const acc_t& acc, const Desc& u, int wr, int wc, int fr, int fq) const {
;     ...
;           for (int bj = 0; bj < 2; ++bj) {
;             const u32x4 pq = pv[m][bj];
;             f32x4 r0, r1;
;             const f32x4& g0 = acc[ai][bj][m][0]; const f32x4& g1 = acc[ai][bj][m][1];
;             r0[0] = sigmoidf_(g0[0]) * bflo(pq.x); r0[1] = sigmoidf_(g0[1]) * bfhi(pq.x); r0[2] = sigmoidf_(g0[2]) * bflo(pq.y); r0[3] = sigmoidf_(g0[3]) * bfhi(pq.y);
;             r1[0] = sigmoidf_(g1[0]) * bflo(pq.z); r1[1] = sigmoidf_(g1[1]) * bfhi(pq.z); r1[2] = sigmoidf_(g1[2]) * bflo(pq.w); r1[3] = sigmoidf_(g1[3]) * bfhi(pq.w);
;             if (!first) { const u32x4 mq = mv[m][bj];
;               r0[0] += bflo(mq.x); r0[1] += bfhi(mq.x); r0[2] += bflo(mq.y); r0[3] += bfhi(mq.y); r1[0] += bflo(mq.z); r1[1] += bfhi(mq.z); r1[2] += bflo(mq.w); r1[3] += bfhi(mq.w); }
;             const u32x4 res = pack8v(r0, r1);
;             if (lastx) *(u32x4*)(M + (size_t)(row0 + ai * HALF + m * 16) * ZS + col0 + bj * HALF) = res;
;             else sp[(16 + (ai * 4 + m) * 2 + bj) * 512] = res;
.LBB0_1216:
	v_cvt_pk_bf16_f32 v168, v172, v173
	v_cvt_pk_bf16_f32 v169, v174, v175
	v_cvt_pk_bf16_f32 v170, v178, v179
	v_cvt_pk_bf16_f32 v171, v180, v181
	s_and_b64 vcc, exec, s[46:47]
	s_mov_b64 s[50:51], -1
	s_cbranch_vccnz .LBB0_1218
	v_add_co_u32_e32 v172, vcc, 0x2a000, v210
	s_mov_b64 s[50:51], 0
	s_nop 0
	v_addc_co_u32_e32 v173, vcc, 0, v211, vcc
	global_store_dwordx4 v[172:173], v[168:171], off

; DI float bflo(unsigned u) { return __uint_as_float(u << 16); }
; DI float bfhi(unsigned u) { return __uint_as_float(u & 0xffff0000u); }
; DI float sigmoidf_(float x) { return __builtin_amdgcn_rcpf(1.f + __builtin_amdgcn_exp2f(-1.4426950408889634f * x)); }
; DI u32x4 pack8v(const f32x4& a, const f32x4& b) { u32x4 w; w.x = pk2(a[0], a[1]); w.y = pk2(a[2], a[3]); w.z = pk2(b[0], b[1]); w.w = pk2(b[2], b[3]); return w; }
;   DI void operator()(const acc_t& acc, const Desc& u, int wr, int wc, int fr, int fq) const {
;     ...
;           for (int bj = 0; bj < 2; ++bj) {
;             const u32x4 pq = pv[m][bj];
;             f32x4 r0, r1;
;             const f32x4& g0 = acc[ai][bj][m][0]; const f32x4& g1 = acc[ai][bj][m][1];
;             r0[0] = sigmoidf_(g0[0]) * bflo(pq.x); r0[1] = sigmoidf_(g0[1]) * bfhi(pq.x); r0[2] = sigmoidf_(g0[2]) * bflo(pq.y); r0[3] = sigmoidf_(g0[3]) * bfhi(pq.y);
;             r1[0] = sigmoidf_(g1[0]) * bflo(pq.z); r1[1] = sigmoidf_(g1[1]) * bfhi(pq.z); r1[2] = sigmoidf_(g1[2]) * bflo(pq.w); r1[3] = sigmoidf_(g1[3]) * bfhi(pq.w);
;             if (!first) { const u32x4 mq = mv[m][bj];
;               r0[0] += bflo(mq.x); r0[1] += bfhi(mq.x); r0[2] += bflo(mq.y); r0[3] += bfhi(mq.y); r1[0] += bflo(mq.z); r1[1] += bfhi(mq.z); r1[2] += bflo(mq.w); r1[3] += bfhi(mq.w); }
;             const u32x4 res = pack8v(r0, r1);
;             if (lastx) *(u32x4*)(M + (size_t)(row0 + ai * HALF + m * 16) * ZS + col0 + bj * HALF) = res;
;             else sp[(16 + (ai * 4 + m) * 2 + bj) * 512] = res;
.LBB0_1222:
	v_cvt_pk_bf16_f32 v164, v168, v169
	v_cvt_pk_bf16_f32 v165, v170, v171
	v_cvt_pk_bf16_f32 v166, v172, v173
	v_cvt_pk_bf16_f32 v167, v174, v175
	s_and_b64 vcc, exec, s[46:47]
	s_mov_b64 s[50:51], -1
	s_cbranch_vccnz .LBB0_1224
	v_add_co_u32_e32 v168, vcc, 0x2c000, v210
	s_mov_b64 s[50:51], 0
	s_nop 0
	v_addc_co_u32_e32 v169, vcc, 0, v211, vcc
	global_store_dwordx4 v[168:169], v[164:167], off

; DI float bflo(unsigned u) { return __uint_as_float(u << 16); }
; DI float bfhi(unsigned u) { return __uint_as_float(u & 0xffff0000u); }
; DI float sigmoidf_(float x) { return __builtin_amdgcn_rcpf(1.f + __builtin_amdgcn_exp2f(-1.4426950408889634f * x)); }
; DI u32x4 pack8v(const f32x4& a, const f32x4& b) { u32x4 w; w.x = pk2(a[0], a[1]); w.y = pk2(a[2], a[3]); w.z = pk2(b[0], b[1]); w.w = pk2(b[2], b[3]); return w; }
;   DI void operator()(const acc_t& acc, const Desc& u, int wr, int wc, int fr, int fq) const {
;     ...
;           for (int bj = 0; bj < 2; ++bj) {
;             const u32x4 pq = pv[m][bj];
;             f32x4 r0, r1;
;             const f32x4& g0 = acc[ai][bj][m][0]; const f32x4& g1 = acc[ai][bj][m][1];
;             r0[0] = sigmoidf_(g0[0]) * bflo(pq.x); r0[1] = sigmoidf_(g0[1]) * bfhi(pq.x); r0[2] = sigmoidf_(g0[2]) * bflo(pq.y); r0[3] = sigmoidf_(g0[3]) * bfhi(pq.y);
;             r1[0] = sigmoidf_(g1[0]) * bflo(pq.z); r1[1] = sigmoidf_(g1[1]) * bfhi(pq.z); r1[2] = sigmoidf_(g1[2]) * bflo(pq.w); r1[3] = sigmoidf_(g1[3]) * bfhi(pq.w);
;             if (!first) { const u32x4 mq = mv[m][bj];
;               r0[0] += bflo(mq.x); r0[1] += bfhi(mq.x); r0[2] += bflo(mq.y); r0[3] += bfhi(mq.y); r1[0] += bflo(mq.z); r1[1] += bfhi(mq.z); r1[2] += bflo(mq.w); r1[3] += bfhi(mq.w); }
;             const u32x4 res = pack8v(r0, r1);
;             if (lastx) *(u32x4*)(M + (size_t)(row0 + ai * HALF + m * 16) * ZS + col0 + bj * HALF) = res;
;             else sp[(16 + (ai * 4 + m) * 2 + bj) * 512] = res;
.LBB0_1228:
	v_cvt_pk_bf16_f32 v160, v164, v165
	v_cvt_pk_bf16_f32 v161, v166, v167
	v_cvt_pk_bf16_f32 v162, v170, v171
	v_cvt_pk_bf16_f32 v163, v172, v173
	s_and_b64 vcc, exec, s[46:47]
	s_mov_b64 s[50:51], -1
	s_cbranch_vccnz .LBB0_1230
	v_add_co_u32_e32 v164, vcc, 0x2e000, v210
	s_mov_b64 s[50:51], 0
	s_nop 0
	v_addc_co_u32_e32 v165, vcc, 0, v211, vcc
	global_store_dwordx4 v[164:165], v[160:163], off

; #define MEMBAR() asm volatile("" ::: "memory")
;   DI void operator()(const acc_t& acc, const Desc& u, int wr, int wc, int fr, int fq) const {
;     ...
;       for (int ai = 0; ai < 2; ++ai) {
;         MEMBAR();
;         u32x4 pv[4][2], mv[4][2];
; #pragma unroll
;         for (int m = 0; m < 4; ++m)
; #pragma unroll
;           for (int bj = 0; bj < 2; ++bj) {
;             pv[m][bj] = sp[((ai * 4 + m) * 2 + bj) * 512];
;             if (!first) mv[m][bj] = sp[(16 + (ai * 4 + m) * 2 + bj) * 512];
;           }
.LBB0_1232:
	s_nop 1
	v_add_co_u32_e32 v160, vcc, 0x10000, v210
	s_nop 1
	v_addc_co_u32_e32 v161, vcc, 0, v211, vcc
	global_load_dwordx4 v[188:191], v[160:161], off
	s_and_b64 vcc, exec, s[44:45]
	s_cbranch_vccnz .LBB0_1234
	v_add_co_u32_e32 v156, vcc, 0x30000, v210
	s_nop 1
	v_addc_co_u32_e32 v157, vcc, 0, v211, vcc
	global_load_dwordx4 v[156:159], v[156:157], off
.LBB0_1234:
	v_add_co_u32_e32 v160, vcc, 0x12000, v210
	s_nop 1
	v_addc_co_u32_e32 v161, vcc, 0, v211, vcc
	global_load_dwordx4 v[184:187], v[160:161], off
	s_and_b64 vcc, exec, s[44:45]
	s_cbranch_vccnz .LBB0_1236
	v_add_co_u32_e32 v152, vcc, 0x32000, v210
	s_nop 1
	v_addc_co_u32_e32 v153, vcc, 0, v211, vcc
	global_load_dwordx4 v[152:155], v[152:153], off
.LBB0_1236:
	v_add_co_u32_e32 v160, vcc, 0x14000, v210
	s_nop 1
	v_addc_co_u32_e32 v161, vcc, 0, v211, vcc
	global_load_dwordx4 v[180:183], v[160:161], off
	s_and_b64 vcc, exec, s[44:45]
	s_cbranch_vccnz .LBB0_1238
	v_add_co_u32_e32 v148, vcc, 0x34000, v210
	s_nop 1
	v_addc_co_u32_e32 v149, vcc, 0, v211, vcc
	global_load_dwordx4 v[148:151], v[148:149], off
.LBB0_1238:
	v_add_co_u32_e32 v160, vcc, 0x16000, v210
	s_nop 1
	v_addc_co_u32_e32 v161, vcc, 0, v211, vcc
	global_load_dwordx4 v[176:179], v[160:161], off
	s_and_b64 vcc, exec, s[44:45]
	s_cbranch_vccnz .LBB0_1240
	v_add_co_u32_e32 v144, vcc, 0x36000, v210
	s_nop 1
	v_addc_co_u32_e32 v145, vcc, 0, v211, vcc
	global_load_dwordx4 v[144:147], v[144:145], off
.LBB0_1240:
	v_add_co_u32_e32 v160, vcc, 0x18000, v210
	s_nop 1
	v_addc_co_u32_e32 v161, vcc, 0, v211, vcc
	global_load_dwordx4 v[172:175], v[160:161], off
	s_and_b64 vcc, exec, s[44:45]
	s_cbranch_vccnz .LBB0_1242
	v_add_co_u32_e32 v140, vcc, 0x38000, v210
	s_nop 1
	v_addc_co_u32_e32 v141, vcc, 0, v211, vcc
	global_load_dwordx4 v[140:143], v[140:141], off
.LBB0_1242:
	v_add_co_u32_e32 v160, vcc, 0x1a000, v210
	s_nop 1
	v_addc_co_u32_e32 v161, vcc, 0, v211, vcc
	global_load_dwordx4 v[168:171], v[160:161], off
	s_and_b64 vcc, exec, s[44:45]
	s_cbranch_vccnz .LBB0_1244
	v_add_co_u32_e32 v136, vcc, 0x3a000, v210
	s_nop 1
	v_addc_co_u32_e32 v137, vcc, 0, v211, vcc
	global_load_dwordx4 v[136:139], v[136:137], off
.LBB0_1244:
	v_add_co_u32_e32 v160, vcc, 0x1c000, v210
	s_nop 1
	v_addc_co_u32_e32 v161, vcc, 0, v211, vcc
	global_load_dwordx4 v[164:167], v[160:161], off
	s_and_b64 vcc, exec, s[44:45]
	s_cbranch_vccnz .LBB0_1246
	v_add_co_u32_e32 v132, vcc, 0x3c000, v210
	s_nop 1
	v_addc_co_u32_e32 v133, vcc, 0, v211, vcc
	global_load_dwordx4 v[132:135], v[132:133], off
.LBB0_1246:
	v_add_co_u32_e32 v160, vcc, 0x1e000, v210
	s_nop 1
	v_addc_co_u32_e32 v161, vcc, 0, v211, vcc
	global_load_dwordx4 v[160:163], v[160:161], off
	s_and_b64 vcc, exec, s[44:45]
	s_cbranch_vccnz .LBB0_1248
	v_add_co_u32_e32 v128, vcc, 0x3e000, v210
	s_nop 1
	v_addc_co_u32_e32 v129, vcc, 0, v211, vcc
	global_load_dwordx4 v[128:131], v[128:129], off

; DI float bflo(unsigned u) { return __uint_as_float(u << 16); }
; DI float bfhi(unsigned u) { return __uint_as_float(u & 0xffff0000u); }
; DI float sigmoidf_(float x) { return __builtin_amdgcn_rcpf(1.f + __builtin_amdgcn_exp2f(-1.4426950408889634f * x)); }
; DI u32x4 pack8v(const f32x4& a, const f32x4& b) { u32x4 w; w.x = pk2(a[0], a[1]); w.y = pk2(a[2], a[3]); w.z = pk2(b[0], b[1]); w.w = pk2(b[2], b[3]); return w; }
;   DI void operator()(const acc_t& acc, const Desc& u, int wr, int wc, int fr, int fq) const {
;     ...
;           for (int bj = 0; bj < 2; ++bj) {
;             const u32x4 pq = pv[m][bj];
;             f32x4 r0, r1;
;             const f32x4& g0 = acc[ai][bj][m][0]; const f32x4& g1 = acc[ai][bj][m][1];
;             r0[0] = sigmoidf_(g0[0]) * bflo(pq.x); r0[1] = sigmoidf_(g0[1]) * bfhi(pq.x); r0[2] = sigmoidf_(g0[2]) * bflo(pq.y); r0[3] = sigmoidf_(g0[3]) * bfhi(pq.y);
;             r1[0] = sigmoidf_(g1[0]) * bflo(pq.z); r1[1] = sigmoidf_(g1[1]) * bfhi(pq.z); r1[2] = sigmoidf_(g1[2]) * bflo(pq.w); r1[3] = sigmoidf_(g1[3]) * bfhi(pq.w);
;             if (!first) { const u32x4 mq = mv[m][bj];
;               r0[0] += bflo(mq.x); r0[1] += bfhi(mq.x); r0[2] += bflo(mq.y); r0[3] += bfhi(mq.y); r1[0] += bflo(mq.z); r1[1] += bfhi(mq.z); r1[2] += bflo(mq.w); r1[3] += bfhi(mq.w); }
;             const u32x4 res = pack8v(r0, r1);
;             if (lastx) *(u32x4*)(M + (size_t)(row0 + ai * HALF + m * 16) * ZS + col0 + bj * HALF) = res;
;             else sp[(16 + (ai * 4 + m) * 2 + bj) * 512] = res;
.LBB0_1250:
	v_cvt_pk_bf16_f32 v156, v214, v215
	v_cvt_pk_bf16_f32 v157, v188, v189
	v_cvt_pk_bf16_f32 v158, v216, v217
	v_cvt_pk_bf16_f32 v159, v190, v191
	s_and_b64 vcc, exec, s[46:47]
	s_mov_b64 s[50:51], -1
	s_cbranch_vccnz .LBB0_1252
	v_add_co_u32_e32 v188, vcc, 0x30000, v210
	s_mov_b64 s[50:51], 0
	s_nop 0
	v_addc_co_u32_e32 v189, vcc, 0, v211, vcc
	global_store_dwordx4 v[188:189], v[156:159], off

; DI float bflo(unsigned u) { return __uint_as_float(u << 16); }
; DI float bfhi(unsigned u) { return __uint_as_float(u & 0xffff0000u); }
; DI float sigmoidf_(float x) { return __builtin_amdgcn_rcpf(1.f + __builtin_amdgcn_exp2f(-1.4426950408889634f * x)); }
; DI u32x4 pack8v(const f32x4& a, const f32x4& b) { u32x4 w; w.x = pk2(a[0], a[1]); w.y = pk2(a[2], a[3]); w.z = pk2(b[0], b[1]); w.w = pk2(b[2], b[3]); return w; }
;   DI void operator()(const acc_t& acc, const Desc& u, int wr, int wc, int fr, int fq) const {
;     ...
;           for (int bj = 0; bj < 2; ++bj) {
;             const u32x4 pq = pv[m][bj];
;             f32x4 r0, r1;
;             const f32x4& g0 = acc[ai][bj][m][0]; const f32x4& g1 = acc[ai][bj][m][1];
;             r0[0] = sigmoidf_(g0[0]) * bflo(pq.x); r0[1] = sigmoidf_(g0[1]) * bfhi(pq.x); r0[2] = sigmoidf_(g0[2]) * bflo(pq.y); r0[3] = sigmoidf_(g0[3]) * bfhi(pq.y);
;             r1[0] = sigmoidf_(g1[0]) * bflo(pq.z); r1[1] = sigmoidf_(g1[1]) * bfhi(pq.z); r1[2] = sigmoidf_(g1[2]) * bflo(pq.w); r1[3] = sigmoidf_(g1[3]) * bfhi(pq.w);
;             if (!first) { const u32x4 mq = mv[m][bj];
;               r0[0] += bflo(mq.x); r0[1] += bfhi(mq.x); r0[2] += bflo(mq.y); r0[3] += bfhi(mq.y); r1[0] += bflo(mq.z); r1[1] += bfhi(mq.z); r1[2] += bflo(mq.w); r1[3] += bfhi(mq.w); }
;             const u32x4 res = pack8v(r0, r1);
;             if (lastx) *(u32x4*)(M + (size_t)(row0 + ai * HALF + m * 16) * ZS + col0 + bj * HALF) = res;
;             else sp[(16 + (ai * 4 + m) * 2 + bj) * 512] = res;
.LBB0_1256:
	v_cvt_pk_bf16_f32 v152, v156, v157
	v_cvt_pk_bf16_f32 v153, v158, v159
	v_cvt_pk_bf16_f32 v154, v184, v185
	v_cvt_pk_bf16_f32 v155, v186, v187
	s_and_b64 vcc, exec, s[46:47]
	s_mov_b64 s[50:51], -1
	s_cbranch_vccnz .LBB0_1258
	v_add_co_u32_e32 v156, vcc, 0x32000, v210
	s_mov_b64 s[50:51], 0
	s_nop 0
	v_addc_co_u32_e32 v157, vcc, 0, v211, vcc
	global_store_dwordx4 v[156:157], v[152:155], off

; DI float bflo(unsigned u) { return __uint_as_float(u << 16); }
; DI float bfhi(unsigned u) { return __uint_as_float(u & 0xffff0000u); }
; DI float sigmoidf_(float x) { return __builtin_amdgcn_rcpf(1.f + __builtin_amdgcn_exp2f(-1.4426950408889634f * x)); }
; DI u32x4 pack8v(const f32x4& a, const f32x4& b) { u32x4 w; w.x = pk2(a[0], a[1]); w.y = pk2(a[2], a[3]); w.z = pk2(b[0], b[1]); w.w = pk2(b[2], b[3]); return w; }
;   DI void operator()(const acc_t& acc, const Desc& u, int wr, int wc, int fr, int fq) const {
;     ...
;           for (int bj = 0; bj < 2; ++bj) {
;             const u32x4 pq = pv[m][bj];
;             f32x4 r0, r1;
;             const f32x4& g0 = acc[ai][bj][m][0]; const f32x4& g1 = acc[ai][bj][m][1];
;             r0[0] = sigmoidf_(g0[0]) * bflo(pq.x); r0[1] = sigmoidf_(g0[1]) * bfhi(pq.x); r0[2] = sigmoidf_(g0[2]) * bflo(pq.y); r0[3] = sigmoidf_(g0[3]) * bfhi(pq.y);
;             r1[0] = sigmoidf_(g1[0]) * bflo(pq.z); r1[1] = sigmoidf_(g1[1]) * bfhi(pq.z); r1[2] = sigmoidf_(g1[2]) * bflo(pq.w); r1[3] = sigmoidf_(g1[3]) * bfhi(pq.w);
;             if (!first) { const u32x4 mq = mv[m][bj];
;               r0[0] += bflo(mq.x); r0[1] += bfhi(mq.x); r0[2] += bflo(mq.y); r0[3] += bfhi(mq.y); r1[0] += bflo(mq.z); r1[1] += bfhi(mq.z); r1[2] += bflo(mq.w); r1[3] += bfhi(mq.w); }
;             const u32x4 res = pack8v(r0, r1);
;             if (lastx) *(u32x4*)(M + (size_t)(row0 + ai * HALF + m * 16) * ZS + col0 + bj * HALF) = res;
;             else sp[(16 + (ai * 4 + m) * 2 + bj) * 512] = res;
.LBB0_1262:
	v_cvt_pk_bf16_f32 v148, v152, v153
	v_cvt_pk_bf16_f32 v149, v154, v155
	v_cvt_pk_bf16_f32 v150, v156, v157
	v_cvt_pk_bf16_f32 v151, v158, v159
	s_and_b64 vcc, exec, s[46:47]
	s_mov_b64 s[50:51], -1
	s_cbranch_vccnz .LBB0_1264
	v_add_co_u32_e32 v152, vcc, 0x34000, v210
	s_mov_b64 s[50:51], 0
	s_nop 0
	v_addc_co_u32_e32 v153, vcc, 0, v211, vcc
	global_store_dwordx4 v[152:153], v[148:151], off

; DI float bflo(unsigned u) { return __uint_as_float(u << 16); }
; DI float bfhi(unsigned u) { return __uint_as_float(u & 0xffff0000u); }
; DI float sigmoidf_(float x) { return __builtin_amdgcn_rcpf(1.f + __builtin_amdgcn_exp2f(-1.4426950408889634f * x)); }
; DI u32x4 pack8v(const f32x4& a, const f32x4& b) { u32x4 w; w.x = pk2(a[0], a[1]); w.y = pk2(a[2], a[3]); w.z = pk2(b[0], b[1]); w.w = pk2(b[2], b[3]); return w; }
;   DI void operator()(const acc_t& acc, const Desc& u, int wr, int wc, int fr, int fq) const {
;     ...
;           for (int bj = 0; bj < 2; ++bj) {
;             const u32x4 pq = pv[m][bj];
;             f32x4 r0, r1;
;             const f32x4& g0 = acc[ai][bj][m][0]; const f32x4& g1 = acc[ai][bj][m][1];
;             r0[0] = sigmoidf_(g0[0]) * bflo(pq.x); r0[1] = sigmoidf_(g0[1]) * bfhi(pq.x); r0[2] = sigmoidf_(g0[2]) * bflo(pq.y); r0[3] = sigmoidf_(g0[3]) * bfhi(pq.y);
;             r1[0] = sigmoidf_(g1[0]) * bflo(pq.z); r1[1] = sigmoidf_(g1[1]) * bfhi(pq.z); r1[2] = sigmoidf_(g1[2]) * bflo(pq.w); r1[3] = sigmoidf_(g1[3]) * bfhi(pq.w);
;             if (!first) { const u32x4 mq = mv[m][bj];
;               r0[0] += bflo(mq.x); r0[1] += bfhi(mq.x); r0[2] += bflo(mq.y); r0[3] += bfhi(mq.y); r1[0] += bflo(mq.z); r1[1] += bfhi(mq.z); r1[2] += bflo(mq.w); r1[3] += bfhi(mq.w); }
;             const u32x4 res = pack8v(r0, r1);
;             if (lastx) *(u32x4*)(M + (size_t)(row0 + ai * HALF + m * 16) * ZS + col0 + bj * HALF) = res;
;             else sp[(16 + (ai * 4 + m) * 2 + bj) * 512] = res;
.LBB0_1268:
	v_cvt_pk_bf16_f32 v144, v148, v149
	v_cvt_pk_bf16_f32 v145, v150, v151
	v_cvt_pk_bf16_f32 v146, v154, v155
	v_cvt_pk_bf16_f32 v147, v156, v157
	s_and_b64 vcc, exec, s[46:47]
	s_mov_b64 s[50:51], -1
	s_cbranch_vccnz .LBB0_1270
	v_add_co_u32_e32 v148, vcc, 0x36000, v210
	s_mov_b64 s[50:51], 0
	s_nop 0
	v_addc_co_u32_e32 v149, vcc, 0, v211, vcc
	global_store_dwordx4 v[148:149], v[144:147], off

; DI float bflo(unsigned u) { return __uint_as_float(u << 16); }
; DI float bfhi(unsigned u) { return __uint_as_float(u & 0xffff0000u); }
; DI float sigmoidf_(float x) { return __builtin_amdgcn_rcpf(1.f + __builtin_amdgcn_exp2f(-1.4426950408889634f * x)); }
; DI u32x4 pack8v(const f32x4& a, const f32x4& b) { u32x4 w; w.x = pk2(a[0], a[1]); w.y = pk2(a[2], a[3]); w.z = pk2(b[0], b[1]); w.w = pk2(b[2], b[3]); return w; }
;   DI void operator()(const acc_t& acc, const Desc& u, int wr, int wc, int fr, int fq) const {
;     ...
;           for (int bj = 0; bj < 2; ++bj) {
;             const u32x4 pq = pv[m][bj];
;             f32x4 r0, r1;
;             const f32x4& g0 = acc[ai][bj][m][0]; const f32x4& g1 = acc[ai][bj][m][1];
;             r0[0] = sigmoidf_(g0[0]) * bflo(pq.x); r0[1] = sigmoidf_(g0[1]) * bfhi(pq.x); r0[2] = sigmoidf_(g0[2]) * bflo(pq.y); r0[3] = sigmoidf_(g0[3]) * bfhi(pq.y);
;             r1[0] = sigmoidf_(g1[0]) * bflo(pq.z); r1[1] = sigmoidf_(g1[1]) * bfhi(pq.z); r1[2] = sigmoidf_(g1[2]) * bflo(pq.w); r1[3] = sigmoidf_(g1[3]) * bfhi(pq.w);
;             if (!first) { const u32x4 mq = mv[m][bj];
;               r0[0] += bflo(mq.x); r0[1] += bfhi(mq.x); r0[2] += bflo(mq.y); r0[3] += bfhi(mq.y); r1[0] += bflo(mq.z); r1[1] += bfhi(mq.z); r1[2] += bflo(mq.w); r1[3] += bfhi(mq.w); }
;             const u32x4 res = pack8v(r0, r1);
;             if (lastx) *(u32x4*)(M + (size_t)(row0 + ai * HALF + m * 16) * ZS + col0 + bj * HALF) = res;
;             else sp[(16 + (ai * 4 + m) * 2 + bj) * 512] = res;
.LBB0_1274:
	v_cvt_pk_bf16_f32 v140, v144, v145
	v_cvt_pk_bf16_f32 v141, v146, v147
	v_cvt_pk_bf16_f32 v142, v148, v149
	v_cvt_pk_bf16_f32 v143, v150, v151
	s_and_b64 vcc, exec, s[46:47]
	s_mov_b64 s[50:51], -1
	s_cbranch_vccnz .LBB0_1276
	v_add_co_u32_e32 v144, vcc, 0x38000, v210
	s_mov_b64 s[50:51], 0
	s_nop 0
	v_addc_co_u32_e32 v145, vcc, 0, v211, vcc
	global_store_dwordx4 v[144:145], v[140:143], off

; DI float bflo(unsigned u) { return __uint_as_float(u << 16); }
; DI float bfhi(unsigned u) { return __uint_as_float(u & 0xffff0000u); }
; DI float sigmoidf_(float x) { return __builtin_amdgcn_rcpf(1.f + __builtin_amdgcn_exp2f(-1.4426950408889634f * x)); }
; DI u32x4 pack8v(const f32x4& a, const f32x4& b) { u32x4 w; w.x = pk2(a[0], a[1]); w.y = pk2(a[2], a[3]); w.z = pk2(b[0], b[1]); w.w = pk2(b[2], b[3]); return w; }
;   DI void operator()(const acc_t& acc, const Desc& u, int wr, int wc, int fr, int fq) const {
;     ...
;           for (int bj = 0; bj < 2; ++bj) {
;             const u32x4 pq = pv[m][bj];
;             f32x4 r0, r1;
;             const f32x4& g0 = acc[ai][bj][m][0]; const f32x4& g1 = acc[ai][bj][m][1];
;             r0[0] = sigmoidf_(g0[0]) * bflo(pq.x); r0[1] = sigmoidf_(g0[1]) * bfhi(pq.x); r0[2] = sigmoidf_(g0[2]) * bflo(pq.y); r0[3] = sigmoidf_(g0[3]) * bfhi(pq.y);
;             r1[0] = sigmoidf_(g1[0]) * bflo(pq.z); r1[1] = sigmoidf_(g1[1]) * bfhi(pq.z); r1[2] = sigmoidf_(g1[2]) * bflo(pq.w); r1[3] = sigmoidf_(g1[3]) * bfhi(pq.w);
;             if (!first) { const u32x4 mq = mv[m][bj];
;               r0[0] += bflo(mq.x); r0[1] += bfhi(mq.x); r0[2] += bflo(mq.y); r0[3] += bfhi(mq.y); r1[0] += bflo(mq.z); r1[1] += bfhi(mq.z); r1[2] += bflo(mq.w); r1[3] += bfhi(mq.w); }
;             const u32x4 res = pack8v(r0, r1);
;             if (lastx) *(u32x4*)(M + (size_t)(row0 + ai * HALF + m * 16) * ZS + col0 + bj * HALF) = res;
;             else sp[(16 + (ai * 4 + m) * 2 + bj) * 512] = res;
.LBB0_1280:
	v_cvt_pk_bf16_f32 v136, v140, v141
	v_cvt_pk_bf16_f32 v137, v142, v143
	v_cvt_pk_bf16_f32 v138, v146, v147
	v_cvt_pk_bf16_f32 v139, v148, v149
	s_and_b64 vcc, exec, s[46:47]
	s_mov_b64 s[50:51], -1
	s_cbranch_vccnz .LBB0_1282
	v_add_co_u32_e32 v140, vcc, 0x3a000, v210
	s_mov_b64 s[50:51], 0
	s_nop 0
	v_addc_co_u32_e32 v141, vcc, 0, v211, vcc
	global_store_dwordx4 v[140:141], v[136:139], off

; DI float bflo(unsigned u) { return __uint_as_float(u << 16); }
; DI float bfhi(unsigned u) { return __uint_as_float(u & 0xffff0000u); }
; DI float sigmoidf_(float x) { return __builtin_amdgcn_rcpf(1.f + __builtin_amdgcn_exp2f(-1.4426950408889634f * x)); }
; DI u32x4 pack8v(const f32x4& a, const f32x4& b) { u32x4 w; w.x = pk2(a[0], a[1]); w.y = pk2(a[2], a[3]); w.z = pk2(b[0], b[1]); w.w = pk2(b[2], b[3]); return w; }
;   DI void operator()(const acc_t& acc, const Desc& u, int wr, int wc, int fr, int fq) const {
;     ...
;           for (int bj = 0; bj < 2; ++bj) {
;             const u32x4 pq = pv[m][bj];
;             f32x4 r0, r1;
;             const f32x4& g0 = acc[ai][bj][m][0]; const f32x4& g1 = acc[ai][bj][m][1];
;             r0[0] = sigmoidf_(g0[0]) * bflo(pq.x); r0[1] = sigmoidf_(g0[1]) * bfhi(pq.x); r0[2] = sigmoidf_(g0[2]) * bflo(pq.y); r0[3] = sigmoidf_(g0[3]) * bfhi(pq.y);
;             r1[0] = sigmoidf_(g1[0]) * bflo(pq.z); r1[1] = sigmoidf_(g1[1]) * bfhi(pq.z); r1[2] = sigmoidf_(g1[2]) * bflo(pq.w); r1[3] = sigmoidf_(g1[3]) * bfhi(pq.w);
;             if (!first) { const u32x4 mq = mv[m][bj];
;               r0[0] += bflo(mq.x); r0[1] += bfhi(mq.x); r0[2] += bflo(mq.y); r0[3] += bfhi(mq.y); r1[0] += bflo(mq.z); r1[1] += bfhi(mq.z); r1[2] += bflo(mq.w); r1[3] += bfhi(mq.w); }
;             const u32x4 res = pack8v(r0, r1);
;             if (lastx) *(u32x4*)(M + (size_t)(row0 + ai * HALF + m * 16) * ZS + col0 + bj * HALF) = res;
;             else sp[(16 + (ai * 4 + m) * 2 + bj) * 512] = res;
.LBB0_1286:
	v_cvt_pk_bf16_f32 v132, v136, v137
	v_cvt_pk_bf16_f32 v133, v138, v139
	v_cvt_pk_bf16_f32 v134, v140, v141
	v_cvt_pk_bf16_f32 v135, v142, v143
	s_and_b64 vcc, exec, s[46:47]
	s_mov_b64 s[50:51], -1
	s_cbranch_vccnz .LBB0_1288
	v_add_co_u32_e32 v136, vcc, 0x3c000, v210
	s_mov_b64 s[50:51], 0
	s_nop 0
	v_addc_co_u32_e32 v137, vcc, 0, v211, vcc
	global_store_dwordx4 v[136:137], v[132:135], off

; DI float bflo(unsigned u) { return __uint_as_float(u << 16); }
; DI float bfhi(unsigned u) { return __uint_as_float(u & 0xffff0000u); }
; DI float sigmoidf_(float x) { return __builtin_amdgcn_rcpf(1.f + __builtin_amdgcn_exp2f(-1.4426950408889634f * x)); }
; DI u32x4 pack8v(const f32x4& a, const f32x4& b) { u32x4 w; w.x = pk2(a[0], a[1]); w.y = pk2(a[2], a[3]); w.z = pk2(b[0], b[1]); w.w = pk2(b[2], b[3]); return w; }
;   DI void operator()(const acc_t& acc, const Desc& u, int wr, int wc, int fr, int fq) const {
;     ...
;           for (int bj = 0; bj < 2; ++bj) {
;             const u32x4 pq = pv[m][bj];
;             f32x4 r0, r1;
;             const f32x4& g0 = acc[ai][bj][m][0]; const f32x4& g1 = acc[ai][bj][m][1];
;             r0[0] = sigmoidf_(g0[0]) * bflo(pq.x); r0[1] = sigmoidf_(g0[1]) * bfhi(pq.x); r0[2] = sigmoidf_(g0[2]) * bflo(pq.y); r0[3] = sigmoidf_(g0[3]) * bfhi(pq.y);
;             r1[0] = sigmoidf_(g1[0]) * bflo(pq.z); r1[1] = sigmoidf_(g1[1]) * bfhi(pq.z); r1[2] = sigmoidf_(g1[2]) * bflo(pq.w); r1[3] = sigmoidf_(g1[3]) * bfhi(pq.w);
;             if (!first) { const u32x4 mq = mv[m][bj];
;               r0[0] += bflo(mq.x); r0[1] += bfhi(mq.x); r0[2] += bflo(mq.y); r0[3] += bfhi(mq.y); r1[0] += bflo(mq.z); r1[1] += bfhi(mq.z); r1[2] += bflo(mq.w); r1[3] += bfhi(mq.w); }
;             const u32x4 res = pack8v(r0, r1);
;             if (lastx) *(u32x4*)(M + (size_t)(row0 + ai * HALF + m * 16) * ZS + col0 + bj * HALF) = res;
;             else sp[(16 + (ai * 4 + m) * 2 + bj) * 512] = res;
.LBB0_1292:
	v_cvt_pk_bf16_f32 v128, v132, v133
	v_cvt_pk_bf16_f32 v129, v134, v135
	v_cvt_pk_bf16_f32 v130, v138, v139
	v_cvt_pk_bf16_f32 v131, v140, v141
	s_and_b64 vcc, exec, s[46:47]
	s_mov_b64 s[44:45], -1
	s_cbranch_vccnz .LBB0_1294
	v_add_co_u32_e32 v132, vcc, 0x3e000, v210
	s_mov_b64 s[44:45], 0
	s_nop 0
	v_addc_co_u32_e32 v133, vcc, 0, v211, vcc
	global_store_dwordx4 v[132:133], v[128:131], off

; DI u32x4 pack8v(const f32x4& a, const f32x4& b) { u32x4 w; w.x = pk2(a[0], a[1]); w.y = pk2(a[2], a[3]); w.z = pk2(b[0], b[1]); w.w = pk2(b[2], b[3]); return w; }
;   DI void operator()(const acc_t& acc, const Desc& u, int wr, int wc, int fr, int fq) const {
;     ...
;     if (!(u.kind & 1)) {
; #pragma unroll
;       for (int ai = 0; ai < 2; ++ai)
; #pragma unroll
;         for (int m = 0; m < 4; ++m)
; #pragma unroll
;           for (int bj = 0; bj < 2; ++bj) sp[((ai * 4 + m) * 2 + bj) * 512] = pack8v(acc[ai][bj][m][0], acc[ai][bj][m][1]);
.LBB0_1297:
	s_and_b64 vcc, exec, s[44:45]
	s_cbranch_vccz .LBB0_1153
	v_cvt_pk_bf16_f32 v108, v108, v109
	v_cvt_pk_bf16_f32 v109, v110, v111
	v_cvt_pk_bf16_f32 v110, v104, v105
	v_add_co_u32_e32 v104, vcc, s22, v210
	v_cvt_pk_bf16_f32 v111, v106, v107
	s_nop 0
	v_addc_co_u32_e32 v105, vcc, 0, v211, vcc
	s_movk_i32 s4, 0x4000
	global_store_dwordx4 v[104:105], v[108:111], off
	v_cvt_pk_bf16_f32 v92, v92, v93
	v_cvt_pk_bf16_f32 v93, v94, v95
	v_add_co_u32_e32 v108, vcc, s4, v210
	s_movk_i32 s4, 0x6000
	s_nop 0
	v_addc_co_u32_e32 v109, vcc, 0, v211, vcc
	v_cvt_pk_bf16_f32 v94, v88, v89
	v_add_co_u32_e32 v88, vcc, s4, v210
	v_cvt_pk_bf16_f32 v95, v90, v91
	s_nop 0
	v_addc_co_u32_e32 v89, vcc, 0, v211, vcc
	s_mov_b32 s4, 0x8000
	global_store_dwordx4 v[88:89], v[92:95], off
	v_cvt_pk_bf16_f32 v76, v76, v77
	v_cvt_pk_bf16_f32 v77, v78, v79
	v_add_co_u32_e32 v92, vcc, s4, v210
	s_mov_b32 s4, 0xa000
	s_nop 0
	v_addc_co_u32_e32 v93, vcc, 0, v211, vcc
	v_cvt_pk_bf16_f32 v78, v72, v73
	v_add_co_u32_e32 v72, vcc, s4, v210
	v_cvt_pk_bf16_f32 v79, v74, v75
	s_nop 0
	v_addc_co_u32_e32 v73, vcc, 0, v211, vcc
	s_mov_b32 s4, 0xc000
	global_store_dwordx4 v[72:73], v[76:79], off
	v_cvt_pk_bf16_f32 v68, v68, v69
	v_cvt_pk_bf16_f32 v69, v70, v71
	v_add_co_u32_e32 v76, vcc, s4, v210
	s_mov_b32 s4, 0xe000
	s_nop 0
	v_addc_co_u32_e32 v77, vcc, 0, v211, vcc
	v_cvt_pk_bf16_f32 v70, v64, v65
	v_add_co_u32_e32 v64, vcc, s4, v210
	s_mov_b32 s4, 0x10000
	s_nop 0
	v_addc_co_u32_e32 v65, vcc, 0, v211, vcc
	v_cvt_pk_bf16_f32 v60, v60, v61
	v_cvt_pk_bf16_f32 v61, v62, v63
	v_cvt_pk_bf16_f32 v62, v56, v57
	v_add_co_u32_e32 v56, vcc, s4, v210
	s_mov_b32 s4, 0x12000
	s_nop 0
	v_addc_co_u32_e32 v57, vcc, 0, v211, vcc
	v_cvt_pk_bf16_f32 v44, v44, v45
	v_cvt_pk_bf16_f32 v45, v46, v47
	v_cvt_pk_bf16_f32 v46, v40, v41
	v_add_co_u32_e32 v40, vcc, s4, v210
	v_cvt_pk_bf16_f32 v47, v42, v43
	s_nop 0
	v_addc_co_u32_e32 v41, vcc, 0, v211, vcc
	s_mov_b32 s4, 0x14000
	global_store_dwordx4 v[40:41], v[44:47], off
	v_cvt_pk_bf16_f32 v28, v28, v29
	v_cvt_pk_bf16_f32 v29, v30, v31
	v_add_co_u32_e32 v44, vcc, s4, v210
	s_mov_b32 s4, 0x16000
	s_nop 0
	v_addc_co_u32_e32 v45, vcc, 0, v211, vcc
	v_cvt_pk_bf16_f32 v30, v24, v25
	v_add_co_u32_e32 v24, vcc, s4, v210
	v_cvt_pk_bf16_f32 v31, v26, v27
	s_nop 0
	v_addc_co_u32_e32 v25, vcc, 0, v211, vcc
	s_mov_b32 s4, 0x18000
	global_store_dwordx4 v[24:25], v[28:31], off
	v_cvt_pk_bf16_f32 v12, v12, v13
	v_cvt_pk_bf16_f32 v13, v14, v15
	v_add_co_u32_e32 v28, vcc, s4, v210
	s_mov_b32 s4, 0x1a000
	s_nop 0
	v_addc_co_u32_e32 v29, vcc, 0, v211, vcc
	v_cvt_pk_bf16_f32 v14, v8, v9
	v_add_co_u32_e32 v8, vcc, s4, v210
	v_cvt_pk_bf16_f32 v15, v10, v11
	s_nop 0
	v_addc_co_u32_e32 v9, vcc, 0, v211, vcc
	s_mov_b32 s4, 0x1c000
	global_store_dwordx4 v[8:9], v[12:15], off
	v_cvt_pk_bf16_f32 v4, v4, v5
	v_cvt_pk_bf16_f32 v5, v6, v7
	v_add_co_u32_e32 v12, vcc, s4, v210
	v_cvt_pk_bf16_f32 v6, v0, v1
	s_nop 0
	v_addc_co_u32_e32 v13, vcc, 0, v211, vcc
	v_add_co_u32_e32 v0, vcc, 0x1e000, v210
	v_cvt_pk_bf16_f32 v124, v124, v125
	v_cvt_pk_bf16_f32 v125, v126, v127
	v_cvt_pk_bf16_f32 v126, v120, v121
	v_cvt_pk_bf16_f32 v127, v122, v123
	v_cvt_pk_bf16_f32 v104, v116, v117
	v_cvt_pk_bf16_f32 v105, v118, v119
	v_cvt_pk_bf16_f32 v106, v112, v113
	v_cvt_pk_bf16_f32 v107, v114, v115
	v_cvt_pk_bf16_f32 v88, v100, v101
	v_cvt_pk_bf16_f32 v89, v102, v103
	v_cvt_pk_bf16_f32 v90, v96, v97
	v_cvt_pk_bf16_f32 v91, v98, v99
	v_cvt_pk_bf16_f32 v72, v84, v85
	v_cvt_pk_bf16_f32 v73, v86, v87
	v_cvt_pk_bf16_f32 v74, v80, v81
	v_cvt_pk_bf16_f32 v75, v82, v83
	v_cvt_pk_bf16_f32 v71, v66, v67
	v_cvt_pk_bf16_f32 v63, v58, v59
	v_cvt_pk_bf16_f32 v40, v52, v53
	v_cvt_pk_bf16_f32 v41, v54, v55
	v_cvt_pk_bf16_f32 v42, v48, v49
	v_cvt_pk_bf16_f32 v43, v50, v51
	v_cvt_pk_bf16_f32 v24, v36, v37
	v_cvt_pk_bf16_f32 v25, v38, v39
	v_cvt_pk_bf16_f32 v26, v32, v33
	v_cvt_pk_bf16_f32 v27, v34, v35
	v_cvt_pk_bf16_f32 v8, v20, v21
	v_cvt_pk_bf16_f32 v9, v22, v23
	v_cvt_pk_bf16_f32 v10, v16, v17
	v_cvt_pk_bf16_f32 v11, v18, v19
	v_cvt_pk_bf16_f32 v7, v2, v3
	v_addc_co_u32_e32 v1, vcc, 0, v211, vcc
	global_store_dwordx4 v[210:211], v[124:127], off
	global_store_dwordx4 v[108:109], v[104:107], off
	global_store_dwordx4 v[92:93], v[88:91], off
	global_store_dwordx4 v[76:77], v[72:75], off
	global_store_dwordx4 v[64:65], v[68:71], off
	global_store_dwordx4 v[56:57], v[60:63], off
	global_store_dwordx4 v[44:45], v[40:43], off
	global_store_dwordx4 v[28:29], v[24:27], off
	global_store_dwordx4 v[12:13], v[8:11], off
	global_store_dwordx4 v[0:1], v[4:7], off
	s_branch .LBB0_1153
